# stack17 variant: the two K LDS-DMA pieces issued in separate QK^T gaps
# baseline (speedup 1.0000x reference)
.Li0_entry:
	v_add_u32_e32 v167, s79, v147
	v_add_u32_e32 v227, s79, v149
	v_add_u32_e32 v194, s79, v151
	v_add_u32_e32 v195, s79, v153
	ds_read_b128 v[64:67], v167
	ds_read_b128 v[188:191], v227
	ds_read_b128 v[228:231], v194
	s_waitcnt lgkmcnt(2)
	v_mfma_f32_32x32x16_bf16 v[64:79], v[64:67], v[80:83], 0
	s_waitcnt lgkmcnt(1)
	v_mfma_f32_32x32x16_bf16 v[64:79], v[188:191], v[84:87], v[64:79]
	ds_read_b128 v[188:191], v195
	s_mov_b64 s[54:55], 0xe404000
	s_add_i32 m0, s96, 0x8000
	v_lshl_add_u64 v[192:193], v[134:135], 0, s[54:55]
	s_nop 0
	global_load_lds_dwordx4 v[192:193], off
	v_cndmask_b32_e64 v173, v113, v121, s[2:3]
	v_cndmask_b32_e64 v172, v112, v120, s[2:3]
	v_cndmask_b32_e64 v177, v121, v113, s[2:3]
	v_cndmask_b32_e64 v176, v120, v112, s[2:3]
	s_waitcnt lgkmcnt(1)
	v_mfma_f32_32x32x16_bf16 v[64:79], v[228:231], v[88:91], v[64:79]
	ds_read_b128 v[228:231], v167 offset:128
	s_mov_b64 s[54:55], 0xe406000
	s_add_i32 m0, s96, 0xa000
	v_lshl_add_u64 v[192:193], v[134:135], 0, s[54:55]
	s_nop 0
	global_load_lds_dwordx4 v[192:193], off
	v_cndmask_b32_e64 v171, v119, v127, s[2:3]
	v_cndmask_b32_e64 v170, v118, v126, s[2:3]
	v_cndmask_b32_e64 v169, v117, v125, s[2:3]
	v_cndmask_b32_e64 v168, v116, v124, s[2:3]
	s_waitcnt lgkmcnt(1)
	v_mfma_f32_32x32x16_bf16 v[64:79], v[188:191], v[92:95], v[64:79]
	ds_read_b128 v[188:191], v227 offset:128
	s_mov_b64 s[54:55], 0xe804000
	s_add_i32 m0, s96, 0xc000
	v_lshl_add_u64 v[192:193], v[134:135], 0, s[54:55]
	s_nop 0
	global_load_lds_dwordx4 v[192:193], off
	v_cndmask_b32_e64 v175, v115, v123, s[2:3]
	v_cndmask_b32_e64 v174, v114, v122, s[2:3]
	v_cndmask_b32_e64 v127, v127, v119, s[2:3]
	v_cndmask_b32_e64 v126, v126, v118, s[2:3]
	s_waitcnt lgkmcnt(1)
	v_mfma_f32_32x32x16_bf16 v[64:79], v[228:231], v[96:99], v[64:79]
	ds_read_b128 v[228:231], v194 offset:128
	s_mov_b64 s[54:55], 0xe806000
	s_add_i32 m0, s96, 0xe000
	v_lshl_add_u64 v[192:193], v[134:135], 0, s[54:55]
	s_nop 0
	global_load_lds_dwordx4 v[192:193], off
	v_cndmask_b32_e64 v125, v125, v117, s[2:3]
	v_cndmask_b32_e64 v124, v124, v116, s[2:3]
	v_cndmask_b32_e64 v179, v123, v115, s[2:3]
	v_cndmask_b32_e64 v178, v122, v114, s[2:3]
	s_waitcnt lgkmcnt(1)
	v_mfma_f32_32x32x16_bf16 v[64:79], v[188:191], v[100:103], v[64:79]
	ds_read_b128 v[188:191], v195 offset:128
	s_cmp_gt_i32 s19, s18
	s_cbranch_scc1 .Li0_kskipa
	v_lshl_add_u64 v[192:193], s[50:51], 0, v[130:131]
	s_mov_b64 s[54:55], 0xc408000
	s_mov_b32 m0, s97
	v_lshl_add_u64 v[192:193], v[192:193], 0, s[54:55]
	s_nop 0
	global_load_lds_dwordx4 v[192:193], off
.Li0_kskipa:
	ds_read_b64_tr_b16 v[180:181], v158 offset:0
	ds_read_b64_tr_b16 v[182:183], v158 offset:0x800
	ds_read_b64_tr_b16 v[184:185], v158 offset:0x200
	ds_read_b64_tr_b16 v[186:187], v158 offset:0xa00
	s_waitcnt lgkmcnt(5)
	v_mfma_f32_32x32x16_bf16 v[64:79], v[228:231], v[104:107], v[64:79]
	s_cmp_gt_i32 s19, s18
	s_cbranch_scc1 .Li0_kskipb
	v_lshl_add_u64 v[192:193], s[50:51], 0, v[130:131]
	s_mov_b64 s[54:55], 0xc40a000
	s_mov_b32 m0, s26
	v_lshl_add_u64 v[192:193], v[192:193], 0, s[54:55]
	s_nop 0
	global_load_lds_dwordx4 v[192:193], off
.Li0_kskipb:
	v_max_f32_e32 v194, v166, v166
	v_max_f32_e32 v195, v164, v164
	v_max_f32_e32 v194, v195, v194
	v_sub_f32_e32 v195, v194, v165
	v_mul_f32_e32 v195, 0x3db504f3, v195
	v_cmp_ge_f32_e32 vcc, s88, v195
	s_waitcnt lgkmcnt(4)
	v_mfma_f32_32x32x16_bf16 v[64:79], v[188:191], v[108:111], v[64:79]
	s_cmp_eq_u64 vcc, exec
	s_cbranch_scc0 .Li0_fb
	v_mov_b32_e32 v166, v165
	s_sub_i32 s52, s83, 64
	s_cmp_le_i32 s52, s25
	s_cbranch_scc1 .Li0_sm
	s_nop 7
	v_add_u32_e32 v112, 0x5b, v162
	v_cmp_gt_u32_e32 vcc, s86, v112
	v_add_u32_e32 v112, s83, v163
	v_add_u32_e32 v112, 0xffffffa1, v112
	v_cndmask_b32_e32 v64, v141, v64, vcc
	v_cmp_lt_u32_e32 vcc, s87, v112
	v_add_u32_e32 v112, 0x59, v162
	s_nop 0
	v_cndmask_b32_e32 v65, v141, v65, vcc
	v_cmp_gt_u32_e32 vcc, s86, v112
	v_add_u32_e32 v112, 0x58, v162
	s_nop 0
	v_cndmask_b32_e32 v66, v141, v66, vcc
	v_cmp_gt_u32_e32 vcc, s86, v112
	v_add_u32_e32 v112, 0x53, v162
	s_nop 0
	v_cndmask_b32_e32 v67, v141, v67, vcc
	v_cmp_gt_u32_e32 vcc, s86, v112
	v_add_u32_e32 v112, 0x52, v162
	s_nop 0
	v_cndmask_b32_e32 v68, v141, v68, vcc
	v_cmp_gt_u32_e32 vcc, s86, v112
	v_add_u32_e32 v112, 0x51, v162
	s_nop 0
	v_cndmask_b32_e32 v69, v141, v69, vcc
	v_cmp_gt_u32_e32 vcc, s86, v112
	v_add_u32_e32 v112, 0x50, v162
	s_nop 0
	v_cndmask_b32_e32 v70, v141, v70, vcc
	v_cmp_gt_u32_e32 vcc, s86, v112
	v_add_u32_e32 v112, 0x4b, v162
	s_nop 0
	v_cndmask_b32_e32 v71, v141, v71, vcc
	v_cmp_gt_u32_e32 vcc, s86, v112
	v_add_u32_e32 v112, 0x4a, v162
	s_nop 0
	v_cndmask_b32_e32 v72, v141, v72, vcc
	v_cmp_gt_u32_e32 vcc, s86, v112
	v_add_u32_e32 v112, 0x49, v162
	s_nop 0
	v_cndmask_b32_e32 v73, v141, v73, vcc
	v_cmp_gt_u32_e32 vcc, s86, v112
	v_add_u32_e32 v112, 0x48, v162
	s_nop 0
	v_cndmask_b32_e32 v74, v141, v74, vcc
	v_cmp_gt_u32_e32 vcc, s86, v112
	v_add_u32_e32 v112, 0x43, v162
	s_nop 0
	v_cndmask_b32_e32 v75, v141, v75, vcc
	v_cmp_gt_u32_e32 vcc, s86, v112
	v_add_u32_e32 v112, 0x42, v162
	s_nop 0
	v_cndmask_b32_e32 v76, v141, v76, vcc
	v_cmp_gt_u32_e32 vcc, s86, v112
	v_add_u32_e32 v112, 0x41, v162
	s_nop 0
	v_cndmask_b32_e32 v77, v141, v77, vcc
	v_cmp_gt_u32_e32 vcc, s86, v112
	v_add_u32_e32 v112, 64, v162
	s_nop 0
	v_cndmask_b32_e32 v78, v141, v78, vcc
	v_cmp_gt_u32_e32 vcc, s86, v112
	s_nop 1
	v_cndmask_b32_e32 v79, v141, v79, vcc

.Li1_entry:
	ds_read_b128 v[64:67], v148
	ds_read_b128 v[188:191], v150
	ds_read_b128 v[228:231], v152
	s_waitcnt lgkmcnt(2)
	v_mfma_f32_32x32x16_bf16 v[64:79], v[64:67], v[80:83], 0
	s_waitcnt lgkmcnt(1)
	v_mfma_f32_32x32x16_bf16 v[64:79], v[188:191], v[84:87], v[64:79]
	ds_read_b128 v[188:191], v154
	s_mov_b64 s[56:57], 0xe408000
	s_mov_b32 m0, s96
	v_lshl_add_u64 v[192:193], v[134:135], 0, s[56:57]
	s_nop 0
	global_load_lds_dwordx4 v[192:193], off
	v_cndmask_b32_e64 v173, v113, v121, s[2:3]
	v_cndmask_b32_e64 v172, v112, v120, s[2:3]
	v_cndmask_b32_e64 v177, v121, v113, s[2:3]
	v_cndmask_b32_e64 v176, v120, v112, s[2:3]
	s_waitcnt lgkmcnt(1)
	v_mfma_f32_32x32x16_bf16 v[64:79], v[228:231], v[88:91], v[64:79]
	ds_read_b128 v[228:231], v148 offset:128
	s_mov_b64 s[56:57], 0xe40a000
	s_mov_b32 m0, s6
	v_lshl_add_u64 v[192:193], v[134:135], 0, s[56:57]
	s_nop 0
	global_load_lds_dwordx4 v[192:193], off
	v_cndmask_b32_e64 v171, v127, v119, s[2:3]
	v_cndmask_b32_e64 v170, v126, v118, s[2:3]
	v_cndmask_b32_e64 v169, v125, v117, s[2:3]
	v_cndmask_b32_e64 v168, v124, v116, s[2:3]
	s_waitcnt lgkmcnt(1)
	v_mfma_f32_32x32x16_bf16 v[64:79], v[188:191], v[92:95], v[64:79]
	ds_read_b128 v[188:191], v150 offset:128
	s_mov_b64 s[56:57], 0xe808000
	s_mov_b32 m0, s7
	v_lshl_add_u64 v[192:193], v[134:135], 0, s[56:57]
	s_nop 0
	global_load_lds_dwordx4 v[192:193], off
	v_cndmask_b32_e64 v175, v115, v123, s[2:3]
	v_cndmask_b32_e64 v174, v114, v122, s[2:3]
	v_cndmask_b32_e64 v127, v119, v127, s[2:3]
	v_cndmask_b32_e64 v126, v118, v126, s[2:3]
	s_waitcnt lgkmcnt(1)
	v_mfma_f32_32x32x16_bf16 v[64:79], v[228:231], v[96:99], v[64:79]
	ds_read_b128 v[228:231], v152 offset:128
	s_mov_b64 s[56:57], 0xe80a000
	s_mov_b32 m0, s24
	v_lshl_add_u64 v[192:193], v[134:135], 0, s[56:57]
	s_nop 0
	global_load_lds_dwordx4 v[192:193], off
	v_cndmask_b32_e64 v125, v117, v125, s[2:3]
	v_cndmask_b32_e64 v124, v116, v124, s[2:3]
	v_cndmask_b32_e64 v179, v123, v115, s[2:3]
	v_cndmask_b32_e64 v178, v122, v114, s[2:3]
	s_waitcnt lgkmcnt(1)
	v_mfma_f32_32x32x16_bf16 v[64:79], v[188:191], v[100:103], v[64:79]
	ds_read_b128 v[188:191], v154 offset:128
	s_add_i32 s56, s19, 1
	s_cmp_gt_i32 s56, s18
	s_cbranch_scc1 .Li1_kskipa
	v_lshl_add_u64 v[192:193], s[50:51], 0, v[130:131]
	s_mov_b64 s[56:57], 0xc40c000
	s_mov_b32 m0, s27
	v_lshl_add_u64 v[192:193], v[192:193], 0, s[56:57]
	s_nop 0
	global_load_lds_dwordx4 v[192:193], off
.Li1_kskipa:
	ds_read_b64_tr_b16 v[180:181], v158 offset:0x8000
	ds_read_b64_tr_b16 v[182:183], v158 offset:0x8800
	ds_read_b64_tr_b16 v[184:185], v158 offset:0x8200
	ds_read_b64_tr_b16 v[186:187], v158 offset:0x8a00
	s_waitcnt lgkmcnt(5)
	v_mfma_f32_32x32x16_bf16 v[64:79], v[228:231], v[104:107], v[64:79]
	s_add_i32 s56, s19, 1
	s_cmp_gt_i32 s56, s18
	s_cbranch_scc1 .Li1_kskipb
	v_lshl_add_u64 v[192:193], s[50:51], 0, v[130:131]
	s_mov_b64 s[56:57], 0xc40e000
	s_mov_b32 m0, s62
	v_lshl_add_u64 v[192:193], v[192:193], 0, s[56:57]
	s_nop 0
	global_load_lds_dwordx4 v[192:193], off
.Li1_kskipb:
	v_max_f32_e32 v194, v128, v128
	v_max_f32_e32 v195, v164, v164
	v_max_f32_e32 v194, v195, v194
	v_sub_f32_e32 v195, v194, v166
	v_mul_f32_e32 v195, 0x3db504f3, v195
	v_cmp_ge_f32_e32 vcc, s88, v195
	s_waitcnt lgkmcnt(4)
	v_mfma_f32_32x32x16_bf16 v[64:79], v[188:191], v[108:111], v[64:79]
	s_cmp_eq_u64 vcc, exec
	s_cbranch_scc0 .Li1_fb
	v_mov_b32_e32 v165, v166
	s_cmp_le_i32 s83, s25
	s_cbranch_scc1 .Li1_sm
	s_nop 7
	v_add_u32_e32 v112, 27, v162
	v_cmp_gt_u32_e32 vcc, s86, v112
	v_add_u32_e32 v112, s83, v163
	v_subrev_u32_e32 v112, 31, v112
	v_cndmask_b32_e32 v64, v141, v64, vcc
	v_cmp_lt_u32_e32 vcc, s87, v112
	v_add_u32_e32 v112, 25, v162
	s_nop 0
	v_cndmask_b32_e32 v65, v141, v65, vcc
	v_cmp_gt_u32_e32 vcc, s86, v112
	v_add_u32_e32 v112, 24, v162
	s_nop 0
	v_cndmask_b32_e32 v66, v141, v66, vcc
	v_cmp_gt_u32_e32 vcc, s86, v112
	v_add_u32_e32 v112, 19, v162
	s_nop 0
	v_cndmask_b32_e32 v67, v141, v67, vcc
	v_cmp_gt_u32_e32 vcc, s86, v112
	v_add_u32_e32 v112, 18, v162
	s_nop 0
	v_cndmask_b32_e32 v68, v141, v68, vcc
	v_cmp_gt_u32_e32 vcc, s86, v112
	v_add_u32_e32 v112, 17, v162
	s_nop 0
	v_cndmask_b32_e32 v69, v141, v69, vcc
	v_cmp_gt_u32_e32 vcc, s86, v112
	v_add_u32_e32 v112, 16, v162
	s_nop 0
	v_cndmask_b32_e32 v70, v141, v70, vcc
	v_cmp_gt_u32_e32 vcc, s86, v112
	v_add_u32_e32 v112, 11, v162
	s_nop 0
	v_cndmask_b32_e32 v71, v141, v71, vcc
	v_cmp_gt_u32_e32 vcc, s86, v112
	v_add_u32_e32 v112, 10, v162
	s_nop 0
	v_cndmask_b32_e32 v72, v141, v72, vcc
	v_cmp_gt_u32_e32 vcc, s86, v112
	v_add_u32_e32 v112, 9, v162
	s_nop 0
	v_cndmask_b32_e32 v73, v141, v73, vcc
	v_cmp_gt_u32_e32 vcc, s86, v112
	v_add_u32_e32 v112, 8, v162
	s_nop 0
	v_cndmask_b32_e32 v74, v141, v74, vcc
	v_cmp_gt_u32_e32 vcc, s86, v112
	v_add_u32_e32 v112, 3, v162
	s_nop 0
	v_cndmask_b32_e32 v75, v141, v75, vcc
	v_cmp_gt_u32_e32 vcc, s86, v112
	v_add_u32_e32 v112, 2, v162
	s_nop 0
	v_cndmask_b32_e32 v76, v141, v76, vcc
	v_cmp_gt_u32_e32 vcc, s86, v112
	v_add_u32_e32 v112, 1, v162
	s_nop 0
	v_cndmask_b32_e32 v77, v141, v77, vcc
	v_cmp_gt_u32_e32 vcc, s86, v112
	s_nop 1
	v_cndmask_b32_e32 v78, v141, v78, vcc
	v_cmp_gt_u32_e32 vcc, s86, v162
	s_nop 1
	v_cndmask_b32_e32 v79, v141, v79, vcc
